# w_out residual GEMM epilogue: pairs of 8-byte XN stores merged into one 16-byte store via v_permlane16_swap (phase 8 instance only); 4 GEMM loops peeled
# speedup vs baseline: 1.0051x; 1.0051x over previous
.LBB0_134:
	v_bfe_u32 v252, v244, 4, 1
	v_mul_u32_u24_e32 v252, 24, v252
	v_mov_b32_e32 v253, 0
	s_load_dwordx2 s[0:1], s[74:75], 0x138
	v_lshl_add_u32 v186, s24, 8, v204
	v_lshl_or_b32 v182, s28, 8, v215
	v_ashrrev_i32_e32 v183, 31, v182
	v_ashrrev_i32_e32 v187, 31, v186
	s_waitcnt lgkmcnt(0)
	v_lshl_add_u64 v[184:185], v[182:183], 2, s[0:1]
	v_lshlrev_b64 v[120:121], 13, v[186:187]
	v_lshl_add_u64 v[234:235], v[184:185], 0, v[120:121]
	global_load_dwordx4 v[218:221], v[234:235], off
	global_load_dwordx4 v[222:225], v[234:235], off offset:64
	global_load_dwordx4 v[226:229], v[234:235], off offset:512
	global_load_dwordx4 v[230:233], v[234:235], off offset:576
	v_or_b32_e32 v196, 16, v186
	v_ashrrev_i32_e32 v197, 31, v196
	v_or_b32_e32 v192, 32, v186
	v_lshlrev_b64 v[120:121], 13, v[196:197]
	v_ashrrev_i32_e32 v193, 31, v192
	v_or_b32_e32 v188, 48, v186
	v_lshl_add_u64 v[212:213], v[184:185], 0, v[120:121]
	v_lshlrev_b64 v[120:121], 13, v[192:193]
	v_ashrrev_i32_e32 v189, 31, v188
	v_lshl_add_u64 v[194:195], v[184:185], 0, v[120:121]
	v_lshlrev_b64 v[120:121], 13, v[188:189]
	v_lshl_add_u64 v[190:191], v[184:185], 0, v[120:121]
	global_load_dwordx4 v[172:175], v[212:213], off
	global_load_dwordx4 v[168:171], v[212:213], off offset:64
	global_load_dwordx4 v[164:167], v[212:213], off offset:512
	global_load_dwordx4 v[160:163], v[212:213], off offset:576
	global_load_dwordx4 v[156:159], v[194:195], off
	global_load_dwordx4 v[152:155], v[194:195], off offset:64
	global_load_dwordx4 v[144:147], v[194:195], off offset:512
	global_load_dwordx4 v[136:139], v[194:195], off offset:576
	global_load_dwordx4 v[148:151], v[190:191], off
	global_load_dwordx4 v[140:143], v[190:191], off offset:64
	global_load_dwordx4 v[132:135], v[190:191], off offset:512
	global_load_dwordx4 v[120:123], v[190:191], off offset:576
	v_lshlrev_b64 v[236:237], 11, v[186:187]
	v_lshl_add_u64 v[236:237], v[236:237], 0, v[182:183]
	s_waitcnt vmcnt(0)
	v_pk_add_f32 v[130:131], v[130:131], v[220:221]
	v_pk_add_f32 v[128:129], v[128:129], v[218:219]
	global_store_dwordx4 v[234:235], v[128:131], off
	v_cvt_pk_bf16_f32 v248, v128, v129
	v_cvt_pk_bf16_f32 v249, v130, v131
	v_mul_f32_e32 v129, v129, v129
	v_fmac_f32_e32 v129, v128, v128
	v_mul_f32_e32 v128, v131, v131
	v_lshl_add_u64 v[220:221], v[236:237], 1, s[12:13]
	v_lshl_add_u64 v[220:221], v[220:221], 0, v[252:253]
	v_fmac_f32_e32 v128, v130, v130
	v_pk_add_f32 v[126:127], v[126:127], v[224:225]
	v_pk_add_f32 v[124:125], v[124:125], v[222:223]
	v_add_f32_e32 v130, v129, v128
	global_store_dwordx4 v[234:235], v[124:127], off offset:64
	v_cvt_pk_bf16_f32 v250, v124, v125
	v_cvt_pk_bf16_f32 v251, v126, v127
	v_mul_f32_e32 v125, v125, v125
	v_fmac_f32_e32 v125, v124, v124
	v_mul_f32_e32 v124, v127, v127
	v_fmac_f32_e32 v124, v126, v126
	v_add_f32_e32 v124, v125, v124
	v_pk_add_f32 v[118:119], v[118:119], v[228:229]
	v_pk_add_f32 v[116:117], v[116:117], v[226:227]
	s_nop 1
	v_permlane16_swap_b32_e32 v248, v250
	v_permlane16_swap_b32_e32 v249, v251
	global_store_dwordx4 v[220:221], v[248:251], off
	s_nop 1
	v_add_f32_e32 v126, v130, v124
	global_store_dwordx4 v[234:235], v[116:119], off offset:512
	v_cvt_pk_bf16_f32 v248, v116, v117
	v_cvt_pk_bf16_f32 v249, v118, v119
	v_mul_f32_e32 v117, v117, v117
	v_fmac_f32_e32 v117, v116, v116
	v_mul_f32_e32 v116, v119, v119
	v_fmac_f32_e32 v116, v118, v118
	v_add_f32_e32 v116, v117, v116
	v_pk_add_f32 v[114:115], v[114:115], v[232:233]
	v_pk_add_f32 v[112:113], v[112:113], v[230:231]
	v_add_f32_e32 v118, v126, v116
	global_store_dwordx4 v[234:235], v[112:115], off offset:576
	v_cvt_pk_bf16_f32 v250, v112, v113
	v_cvt_pk_bf16_f32 v251, v114, v115
	v_mul_f32_e32 v113, v113, v113
	v_fmac_f32_e32 v113, v112, v112
	v_mul_f32_e32 v112, v115, v115
	v_fmac_f32_e32 v112, v114, v114
	v_and_b32_e32 v114, 64, v244
	v_add_f32_e32 v112, v113, v112
	v_xor_b32_e32 v113, 16, v244
	v_add_u32_e32 v114, 64, v114
	v_cmp_lt_i32_e32 vcc, v113, v114
	v_add_f32_e32 v112, v118, v112
	s_nop 1
	v_permlane16_swap_b32_e32 v248, v250
	v_permlane16_swap_b32_e32 v249, v251
	global_store_dwordx4 v[220:221], v[248:251], off offset:256
	s_nop 1
	v_cndmask_b32_e32 v113, v244, v113, vcc
	v_lshlrev_b32_e32 v126, 2, v113
	ds_bpermute_b32 v113, v126, v112
	s_waitcnt lgkmcnt(0)
	v_add_f32_e32 v112, v112, v113
	v_xor_b32_e32 v113, 32, v244
	v_cmp_lt_i32_e32 vcc, v113, v114
	s_nop 1
	v_cndmask_b32_e32 v113, v244, v113, vcc
	v_lshlrev_b32_e32 v127, 2, v113
	ds_bpermute_b32 v113, v127, v112
	s_and_saveexec_b64 s[24:25], s[6:7]
	s_cbranch_execz .LBB0_136
	v_lshl_add_u64 v[114:115], v[186:187], 2, s[80:81]
	s_waitcnt lgkmcnt(0)
	v_add_f32_e32 v112, v112, v113
	global_atomic_add_f32 v[114:115], v112, off
.LBB0_136:
	s_or_b64 exec, exec, s[24:25]
	v_pk_add_f32 v[110:111], v[110:111], v[174:175]
	v_pk_add_f32 v[108:109], v[108:109], v[172:173]
	s_waitcnt lgkmcnt(0)
	v_lshlrev_b64 v[112:113], 11, v[196:197]
	global_store_dwordx4 v[212:213], v[108:111], off
	v_cvt_pk_bf16_f32 v248, v108, v109
	v_lshl_add_u64 v[112:113], v[112:113], 0, v[182:183]
	v_mul_f32_e32 v109, v109, v109
	v_fmac_f32_e32 v109, v108, v108
	v_mul_f32_e32 v108, v111, v111
	v_cvt_pk_bf16_f32 v249, v110, v111
	v_lshl_add_u64 v[112:113], v[112:113], 1, s[12:13]
	v_lshl_add_u64 v[112:113], v[112:113], 0, v[252:253]
	v_fmac_f32_e32 v108, v110, v110
	v_pk_add_f32 v[106:107], v[106:107], v[170:171]
	v_pk_add_f32 v[104:105], v[104:105], v[168:169]
	v_add_f32_e32 v110, v109, v108
	global_store_dwordx4 v[212:213], v[104:107], off offset:64
	v_cvt_pk_bf16_f32 v250, v104, v105
	v_pk_add_f32 v[102:103], v[102:103], v[166:167]
	v_mul_f32_e32 v105, v105, v105
	v_fmac_f32_e32 v105, v104, v104
	v_mul_f32_e32 v104, v107, v107
	v_fmac_f32_e32 v104, v106, v106
	v_pk_add_f32 v[100:101], v[100:101], v[164:165]
	v_cvt_pk_bf16_f32 v251, v106, v107
	v_add_f32_e32 v104, v105, v104
	v_mul_f32_e32 v105, v101, v101
	v_mul_f32_e32 v106, v103, v103
	v_fmac_f32_e32 v105, v100, v100
	v_fmac_f32_e32 v106, v102, v102
	v_add_f32_e32 v104, v110, v104
	v_add_f32_e32 v105, v105, v106
	s_nop 1
	v_permlane16_swap_b32_e32 v248, v250
	v_permlane16_swap_b32_e32 v249, v251
	global_store_dwordx4 v[112:113], v[248:251], off
	s_nop 1
	v_add_f32_e32 v108, v104, v105
	v_pk_add_f32 v[106:107], v[98:99], v[162:163]
	v_pk_add_f32 v[104:105], v[96:97], v[160:161]
	v_mul_f32_e32 v97, v107, v107
	v_mul_f32_e32 v96, v105, v105
	v_fmac_f32_e32 v96, v104, v104
	v_fmac_f32_e32 v97, v106, v106
	v_add_f32_e32 v96, v96, v97
	v_add_f32_e32 v98, v108, v96
	ds_bpermute_b32 v99, v126, v98
	v_cvt_pk_bf16_f32 v248, v100, v101
	v_cvt_pk_bf16_f32 v249, v102, v103
	global_store_dwordx4 v[212:213], v[100:103], off offset:512
	s_waitcnt lgkmcnt(0)
	v_add_f32_e32 v96, v98, v99
	ds_bpermute_b32 v97, v127, v96
	v_cvt_pk_bf16_f32 v250, v104, v105
	v_cvt_pk_bf16_f32 v251, v106, v107
	global_store_dwordx4 v[212:213], v[104:107], off offset:576
	s_nop 1
	v_permlane16_swap_b32_e32 v248, v250
	v_permlane16_swap_b32_e32 v249, v251
	global_store_dwordx4 v[112:113], v[248:251], off offset:256
	s_nop 1
	s_and_saveexec_b64 s[24:25], s[6:7]
	s_cbranch_execz .LBB0_138
	v_lshl_add_u64 v[98:99], v[196:197], 2, s[80:81]
	s_waitcnt lgkmcnt(0)
	v_add_f32_e32 v96, v96, v97
	global_atomic_add_f32 v[98:99], v96, off
.LBB0_138:
	s_or_b64 exec, exec, s[24:25]
	v_pk_add_f32 v[94:95], v[94:95], v[158:159]
	v_pk_add_f32 v[92:93], v[92:93], v[156:157]
	s_waitcnt lgkmcnt(0)
	v_lshlrev_b64 v[96:97], 11, v[192:193]
	global_store_dwordx4 v[194:195], v[92:95], off
	v_cvt_pk_bf16_f32 v248, v92, v93
	v_lshl_add_u64 v[96:97], v[96:97], 0, v[182:183]
	v_mul_f32_e32 v93, v93, v93
	v_fmac_f32_e32 v93, v92, v92
	v_mul_f32_e32 v92, v95, v95
	v_cvt_pk_bf16_f32 v249, v94, v95
	v_lshl_add_u64 v[96:97], v[96:97], 1, s[12:13]
	v_lshl_add_u64 v[96:97], v[96:97], 0, v[252:253]
	v_fmac_f32_e32 v92, v94, v94
	v_pk_add_f32 v[90:91], v[90:91], v[154:155]
	v_pk_add_f32 v[88:89], v[88:89], v[152:153]
	v_add_f32_e32 v94, v93, v92
	global_store_dwordx4 v[194:195], v[88:91], off offset:64
	v_cvt_pk_bf16_f32 v250, v88, v89
	v_pk_add_f32 v[86:87], v[86:87], v[146:147]
	v_mul_f32_e32 v89, v89, v89
	v_fmac_f32_e32 v89, v88, v88
	v_mul_f32_e32 v88, v91, v91
	v_fmac_f32_e32 v88, v90, v90
	v_pk_add_f32 v[84:85], v[84:85], v[144:145]
	v_cvt_pk_bf16_f32 v251, v90, v91
	v_add_f32_e32 v88, v89, v88
	v_mul_f32_e32 v89, v85, v85
	v_mul_f32_e32 v90, v87, v87
	v_fmac_f32_e32 v89, v84, v84
	v_fmac_f32_e32 v90, v86, v86
	v_add_f32_e32 v88, v94, v88
	v_add_f32_e32 v89, v89, v90
	s_nop 1
	v_permlane16_swap_b32_e32 v248, v250
	v_permlane16_swap_b32_e32 v249, v251
	global_store_dwordx4 v[96:97], v[248:251], off
	s_nop 1
	v_add_f32_e32 v92, v88, v89
	v_pk_add_f32 v[90:91], v[82:83], v[138:139]
	v_pk_add_f32 v[88:89], v[80:81], v[136:137]
	v_mul_f32_e32 v81, v91, v91
	v_mul_f32_e32 v80, v89, v89
	v_fmac_f32_e32 v80, v88, v88
	v_fmac_f32_e32 v81, v90, v90
	v_add_f32_e32 v80, v80, v81
	v_add_f32_e32 v82, v92, v80
	ds_bpermute_b32 v83, v126, v82
	v_cvt_pk_bf16_f32 v248, v84, v85
	v_cvt_pk_bf16_f32 v249, v86, v87
	global_store_dwordx4 v[194:195], v[84:87], off offset:512
	s_waitcnt lgkmcnt(0)
	v_add_f32_e32 v80, v82, v83
	ds_bpermute_b32 v81, v127, v80
	v_cvt_pk_bf16_f32 v250, v88, v89
	v_cvt_pk_bf16_f32 v251, v90, v91
	global_store_dwordx4 v[194:195], v[88:91], off offset:576
	s_nop 1
	v_permlane16_swap_b32_e32 v248, v250
	v_permlane16_swap_b32_e32 v249, v251
	global_store_dwordx4 v[96:97], v[248:251], off offset:256
	s_nop 1
	s_and_saveexec_b64 s[24:25], s[6:7]
	s_cbranch_execz .LBB0_140
	v_lshl_add_u64 v[82:83], v[192:193], 2, s[80:81]
	s_waitcnt lgkmcnt(0)
	v_add_f32_e32 v80, v80, v81
	global_atomic_add_f32 v[82:83], v80, off
.LBB0_140:
	s_or_b64 exec, exec, s[24:25]
	v_pk_add_f32 v[78:79], v[78:79], v[150:151]
	v_pk_add_f32 v[76:77], v[76:77], v[148:149]
	s_waitcnt lgkmcnt(0)
	v_lshlrev_b64 v[80:81], 11, v[188:189]
	global_store_dwordx4 v[190:191], v[76:79], off
	v_cvt_pk_bf16_f32 v248, v76, v77
	v_lshl_add_u64 v[80:81], v[80:81], 0, v[182:183]
	v_mul_f32_e32 v77, v77, v77
	v_fmac_f32_e32 v77, v76, v76
	v_mul_f32_e32 v76, v79, v79
	v_cvt_pk_bf16_f32 v249, v78, v79
	v_lshl_add_u64 v[80:81], v[80:81], 1, s[12:13]
	v_lshl_add_u64 v[80:81], v[80:81], 0, v[252:253]
	v_fmac_f32_e32 v76, v78, v78
	v_pk_add_f32 v[74:75], v[74:75], v[142:143]
	v_pk_add_f32 v[72:73], v[72:73], v[140:141]
	v_add_f32_e32 v78, v77, v76
	global_store_dwordx4 v[190:191], v[72:75], off offset:64
	v_cvt_pk_bf16_f32 v250, v72, v73
	v_pk_add_f32 v[70:71], v[70:71], v[134:135]
	v_mul_f32_e32 v73, v73, v73
	v_fmac_f32_e32 v73, v72, v72
	v_mul_f32_e32 v72, v75, v75
	v_fmac_f32_e32 v72, v74, v74
	v_pk_add_f32 v[68:69], v[68:69], v[132:133]
	v_cvt_pk_bf16_f32 v251, v74, v75
	v_add_f32_e32 v72, v73, v72
	v_mul_f32_e32 v73, v69, v69
	v_mul_f32_e32 v74, v71, v71
	v_fmac_f32_e32 v73, v68, v68
	v_fmac_f32_e32 v74, v70, v70
	v_add_f32_e32 v72, v78, v72
	v_add_f32_e32 v73, v73, v74
	s_nop 1
	v_permlane16_swap_b32_e32 v248, v250
	v_permlane16_swap_b32_e32 v249, v251
	global_store_dwordx4 v[80:81], v[248:251], off
	s_nop 1
	v_add_f32_e32 v76, v72, v73
	v_pk_add_f32 v[74:75], v[66:67], v[122:123]
	v_pk_add_f32 v[72:73], v[64:65], v[120:121]
	v_mul_f32_e32 v65, v75, v75
	v_mul_f32_e32 v64, v73, v73
	v_fmac_f32_e32 v64, v72, v72
	v_fmac_f32_e32 v65, v74, v74
	v_add_f32_e32 v64, v64, v65
	v_add_f32_e32 v66, v76, v64
	ds_bpermute_b32 v67, v126, v66
	v_cvt_pk_bf16_f32 v248, v68, v69
	v_cvt_pk_bf16_f32 v249, v70, v71
	global_store_dwordx4 v[190:191], v[68:71], off offset:512
	s_waitcnt lgkmcnt(0)
	v_add_f32_e32 v64, v66, v67
	ds_bpermute_b32 v65, v127, v64
	v_cvt_pk_bf16_f32 v250, v72, v73
	v_cvt_pk_bf16_f32 v251, v74, v75
	global_store_dwordx4 v[190:191], v[72:75], off offset:576
	s_nop 1
	v_permlane16_swap_b32_e32 v248, v250
	v_permlane16_swap_b32_e32 v249, v251
	global_store_dwordx4 v[80:81], v[248:251], off offset:256
	s_nop 1
	s_and_saveexec_b64 s[24:25], s[6:7]
	s_cbranch_execz .LBB0_142
	v_lshl_add_u64 v[66:67], v[188:189], 2, s[80:81]
	s_waitcnt lgkmcnt(0)
	v_add_f32_e32 v64, v64, v65
	global_atomic_add_f32 v[66:67], v64, off
.LBB0_142:
	s_or_b64 exec, exec, s[24:25]
	v_add_u32_e32 v124, 0x80, v186
	v_ashrrev_i32_e32 v125, 31, v124
	s_waitcnt lgkmcnt(0)
	v_lshlrev_b64 v[64:65], 13, v[124:125]
	v_lshl_add_u64 v[144:145], v[184:185], 0, v[64:65]
	global_load_dwordx4 v[128:131], v[144:145], off
	global_load_dwordx4 v[132:135], v[144:145], off offset:64
	global_load_dwordx4 v[136:139], v[144:145], off offset:512
	global_load_dwordx4 v[140:143], v[144:145], off offset:576
	v_add_u32_e32 v120, 0x90, v186
	v_add_u32_e32 v116, 0xa0, v186
	v_add_u32_e32 v112, 0xb0, v186
	v_ashrrev_i32_e32 v121, 31, v120
	v_ashrrev_i32_e32 v117, 31, v116
	v_ashrrev_i32_e32 v113, 31, v112
	v_lshlrev_b64 v[64:65], 13, v[120:121]
	v_lshlrev_b64 v[66:67], 13, v[116:117]
	v_lshlrev_b64 v[68:69], 13, v[112:113]
	v_lshl_add_u64 v[122:123], v[184:185], 0, v[64:65]
	v_lshl_add_u64 v[118:119], v[184:185], 0, v[66:67]
	v_lshl_add_u64 v[114:115], v[184:185], 0, v[68:69]
	global_load_dwordx4 v[108:111], v[122:123], off
	global_load_dwordx4 v[104:107], v[122:123], off offset:64
	global_load_dwordx4 v[100:103], v[122:123], off offset:512
	global_load_dwordx4 v[96:99], v[122:123], off offset:576
	global_load_dwordx4 v[92:95], v[118:119], off
	global_load_dwordx4 v[88:91], v[118:119], off offset:64
	global_load_dwordx4 v[84:87], v[118:119], off offset:512
	global_load_dwordx4 v[80:83], v[118:119], off offset:576
	global_load_dwordx4 v[76:79], v[114:115], off
	global_load_dwordx4 v[72:75], v[114:115], off offset:64
	global_load_dwordx4 v[68:71], v[114:115], off offset:512
	global_load_dwordx4 v[64:67], v[114:115], off offset:576
	v_lshlrev_b64 v[146:147], 11, v[124:125]
	v_lshl_add_u64 v[146:147], v[146:147], 0, v[182:183]
	v_lshl_add_u64 v[146:147], v[146:147], 1, s[12:13]
	v_lshl_add_u64 v[146:147], v[146:147], 0, v[252:253]
	s_waitcnt vmcnt(15)
	v_pk_add_f32 v[62:63], v[62:63], v[130:131]
	v_pk_add_f32 v[60:61], v[60:61], v[128:129]
	s_waitcnt vmcnt(14)
	v_pk_add_f32 v[58:59], v[58:59], v[134:135]
	v_pk_add_f32 v[56:57], v[56:57], v[132:133]
	s_waitcnt vmcnt(13)
	v_pk_add_f32 v[54:55], v[54:55], v[138:139]
	v_pk_add_f32 v[52:53], v[52:53], v[136:137]
	s_waitcnt vmcnt(12)
	v_pk_add_f32 v[128:129], v[48:49], v[140:141]
	global_store_dwordx4 v[144:145], v[60:63], off
	v_cvt_pk_bf16_f32 v248, v60, v61
	v_cvt_pk_bf16_f32 v249, v62, v63
	v_mul_f32_e32 v61, v61, v61
	v_mul_f32_e32 v63, v63, v63
	v_mul_f32_e32 v132, v57, v57
	v_mul_f32_e32 v133, v59, v59
	v_pk_add_f32 v[130:131], v[50:51], v[142:143]
	v_mul_f32_e32 v134, v53, v53
	v_mul_f32_e32 v135, v55, v55
	v_fmac_f32_e32 v61, v60, v60
	v_fmac_f32_e32 v63, v62, v62
	v_fmac_f32_e32 v132, v56, v56
	v_fmac_f32_e32 v133, v58, v58
	v_cvt_pk_bf16_f32 v250, v56, v57
	v_mul_f32_e32 v136, v129, v129
	v_mul_f32_e32 v137, v131, v131
	v_fmac_f32_e32 v134, v52, v52
	v_fmac_f32_e32 v135, v54, v54
	v_add_f32_e32 v48, v61, v63
	v_add_f32_e32 v49, v132, v133
	v_cvt_pk_bf16_f32 v251, v58, v59
	global_store_dwordx4 v[144:145], v[56:59], off offset:64
	s_nop 1
	v_permlane16_swap_b32_e32 v248, v250
	v_permlane16_swap_b32_e32 v249, v251
	global_store_dwordx4 v[146:147], v[248:251], off
	s_nop 1
	v_fmac_f32_e32 v136, v128, v128
	v_fmac_f32_e32 v137, v130, v130
	v_add_f32_e32 v50, v134, v135
	v_add_f32_e32 v48, v48, v49
	v_add_f32_e32 v48, v48, v50
	v_add_f32_e32 v49, v136, v137
	v_add_f32_e32 v50, v48, v49
	ds_bpermute_b32 v51, v126, v50
	v_cvt_pk_bf16_f32 v248, v52, v53
	v_cvt_pk_bf16_f32 v249, v54, v55
	global_store_dwordx4 v[144:145], v[52:55], off offset:512
	s_waitcnt lgkmcnt(0)
	v_add_f32_e32 v48, v50, v51
	ds_bpermute_b32 v49, v127, v48
	v_cvt_pk_bf16_f32 v250, v128, v129
	v_cvt_pk_bf16_f32 v251, v130, v131
	global_store_dwordx4 v[144:145], v[128:131], off offset:576
	s_nop 1
	v_permlane16_swap_b32_e32 v248, v250
	v_permlane16_swap_b32_e32 v249, v251
	global_store_dwordx4 v[146:147], v[248:251], off offset:256
	s_nop 1
	s_and_saveexec_b64 s[24:25], s[6:7]
	s_cbranch_execz .LBB0_144
	v_lshl_add_u64 v[50:51], v[124:125], 2, s[80:81]
	s_waitcnt lgkmcnt(0)
	v_add_f32_e32 v48, v48, v49
	global_atomic_add_f32 v[50:51], v48, off
.LBB0_144:
	s_or_b64 exec, exec, s[24:25]
	s_waitcnt vmcnt(19)
	v_pk_add_f32 v[46:47], v[46:47], v[110:111]
	v_pk_add_f32 v[44:45], v[44:45], v[108:109]
	s_waitcnt lgkmcnt(0)
	v_lshlrev_b64 v[48:49], 11, v[120:121]
	global_store_dwordx4 v[122:123], v[44:47], off
	v_cvt_pk_bf16_f32 v248, v44, v45
	v_lshl_add_u64 v[48:49], v[48:49], 0, v[182:183]
	v_mul_f32_e32 v45, v45, v45
	v_fmac_f32_e32 v45, v44, v44
	v_mul_f32_e32 v44, v47, v47
	v_cvt_pk_bf16_f32 v249, v46, v47
	v_lshl_add_u64 v[48:49], v[48:49], 1, s[12:13]
	v_lshl_add_u64 v[48:49], v[48:49], 0, v[252:253]
	v_fmac_f32_e32 v44, v46, v46
	s_waitcnt vmcnt(19)
	v_pk_add_f32 v[42:43], v[42:43], v[106:107]
	v_pk_add_f32 v[40:41], v[40:41], v[104:105]
	v_add_f32_e32 v46, v45, v44
	global_store_dwordx4 v[122:123], v[40:43], off offset:64
	v_cvt_pk_bf16_f32 v250, v40, v41
	s_waitcnt vmcnt(20)
	v_pk_add_f32 v[38:39], v[38:39], v[102:103]
	v_mul_f32_e32 v41, v41, v41
	v_fmac_f32_e32 v41, v40, v40
	v_mul_f32_e32 v40, v43, v43
	v_fmac_f32_e32 v40, v42, v42
	v_pk_add_f32 v[36:37], v[36:37], v[100:101]
	v_cvt_pk_bf16_f32 v251, v42, v43
	v_add_f32_e32 v40, v41, v40
	v_mul_f32_e32 v41, v37, v37
	v_mul_f32_e32 v42, v39, v39
	v_fmac_f32_e32 v41, v36, v36
	v_fmac_f32_e32 v42, v38, v38
	v_add_f32_e32 v40, v46, v40
	v_add_f32_e32 v41, v41, v42
	s_nop 1
	v_permlane16_swap_b32_e32 v248, v250
	v_permlane16_swap_b32_e32 v249, v251
	global_store_dwordx4 v[48:49], v[248:251], off
	s_nop 1
	v_add_f32_e32 v44, v40, v41
	s_waitcnt vmcnt(20)
	v_pk_add_f32 v[42:43], v[34:35], v[98:99]
	v_pk_add_f32 v[40:41], v[32:33], v[96:97]
	v_mul_f32_e32 v33, v43, v43
	v_mul_f32_e32 v32, v41, v41
	v_fmac_f32_e32 v32, v40, v40
	v_fmac_f32_e32 v33, v42, v42
	v_add_f32_e32 v32, v32, v33
	v_add_f32_e32 v34, v44, v32
	ds_bpermute_b32 v35, v126, v34
	v_cvt_pk_bf16_f32 v248, v36, v37
	v_cvt_pk_bf16_f32 v249, v38, v39
	global_store_dwordx4 v[122:123], v[36:39], off offset:512
	s_waitcnt lgkmcnt(0)
	v_add_f32_e32 v32, v34, v35
	ds_bpermute_b32 v33, v127, v32
	v_cvt_pk_bf16_f32 v250, v40, v41
	v_cvt_pk_bf16_f32 v251, v42, v43
	global_store_dwordx4 v[122:123], v[40:43], off offset:576
	s_nop 1
	v_permlane16_swap_b32_e32 v248, v250
	v_permlane16_swap_b32_e32 v249, v251
	global_store_dwordx4 v[48:49], v[248:251], off offset:256
	s_nop 1
	s_and_saveexec_b64 s[24:25], s[6:7]
	s_cbranch_execz .LBB0_146
	v_lshl_add_u64 v[34:35], v[120:121], 2, s[80:81]
	s_waitcnt lgkmcnt(0)
	v_add_f32_e32 v32, v32, v33
	global_atomic_add_f32 v[34:35], v32, off
.LBB0_146:
	s_or_b64 exec, exec, s[24:25]
	s_waitcnt vmcnt(23)
	v_pk_add_f32 v[30:31], v[30:31], v[94:95]
	v_pk_add_f32 v[28:29], v[28:29], v[92:93]
	s_waitcnt lgkmcnt(0)
	v_lshlrev_b64 v[32:33], 11, v[116:117]
	global_store_dwordx4 v[118:119], v[28:31], off
	v_cvt_pk_bf16_f32 v248, v28, v29
	v_lshl_add_u64 v[32:33], v[32:33], 0, v[182:183]
	v_mul_f32_e32 v29, v29, v29
	v_fmac_f32_e32 v29, v28, v28
	v_mul_f32_e32 v28, v31, v31
	v_cvt_pk_bf16_f32 v249, v30, v31
	v_lshl_add_u64 v[32:33], v[32:33], 1, s[12:13]
	v_lshl_add_u64 v[32:33], v[32:33], 0, v[252:253]
	v_fmac_f32_e32 v28, v30, v30
	s_waitcnt vmcnt(23)
	v_pk_add_f32 v[26:27], v[26:27], v[90:91]
	v_pk_add_f32 v[24:25], v[24:25], v[88:89]
	v_add_f32_e32 v30, v29, v28
	global_store_dwordx4 v[118:119], v[24:27], off offset:64
	v_cvt_pk_bf16_f32 v250, v24, v25
	s_waitcnt vmcnt(24)
	v_pk_add_f32 v[22:23], v[22:23], v[86:87]
	v_mul_f32_e32 v25, v25, v25
	v_fmac_f32_e32 v25, v24, v24
	v_mul_f32_e32 v24, v27, v27
	v_fmac_f32_e32 v24, v26, v26
	v_pk_add_f32 v[20:21], v[20:21], v[84:85]
	v_cvt_pk_bf16_f32 v251, v26, v27
	v_add_f32_e32 v24, v25, v24
	v_mul_f32_e32 v25, v21, v21
	v_mul_f32_e32 v26, v23, v23
	v_fmac_f32_e32 v25, v20, v20
	v_fmac_f32_e32 v26, v22, v22
	v_add_f32_e32 v24, v30, v24
	v_add_f32_e32 v25, v25, v26
	s_nop 1
	v_permlane16_swap_b32_e32 v248, v250
	v_permlane16_swap_b32_e32 v249, v251
	global_store_dwordx4 v[32:33], v[248:251], off
	s_nop 1
	v_add_f32_e32 v28, v24, v25
	s_waitcnt vmcnt(24)
	v_pk_add_f32 v[26:27], v[18:19], v[82:83]
	v_pk_add_f32 v[24:25], v[16:17], v[80:81]
	v_mul_f32_e32 v17, v27, v27
	v_mul_f32_e32 v16, v25, v25
	v_fmac_f32_e32 v16, v24, v24
	v_fmac_f32_e32 v17, v26, v26
	v_add_f32_e32 v16, v16, v17
	v_add_f32_e32 v18, v28, v16
	ds_bpermute_b32 v19, v126, v18
	v_cvt_pk_bf16_f32 v248, v20, v21
	v_cvt_pk_bf16_f32 v249, v22, v23
	global_store_dwordx4 v[118:119], v[20:23], off offset:512
	s_waitcnt lgkmcnt(0)
	v_add_f32_e32 v16, v18, v19
	ds_bpermute_b32 v17, v127, v16
	v_cvt_pk_bf16_f32 v250, v24, v25
	v_cvt_pk_bf16_f32 v251, v26, v27
	global_store_dwordx4 v[118:119], v[24:27], off offset:576
	s_nop 1
	v_permlane16_swap_b32_e32 v248, v250
	v_permlane16_swap_b32_e32 v249, v251
	global_store_dwordx4 v[32:33], v[248:251], off offset:256
	s_nop 1
	s_and_saveexec_b64 s[24:25], s[6:7]
	s_cbranch_execz .LBB0_148
	v_lshl_add_u64 v[18:19], v[116:117], 2, s[80:81]
	s_waitcnt lgkmcnt(0)
	v_add_f32_e32 v16, v16, v17
	global_atomic_add_f32 v[18:19], v16, off
.LBB0_148:
	s_or_b64 exec, exec, s[24:25]
	s_waitcnt vmcnt(27)
	v_pk_add_f32 v[14:15], v[14:15], v[78:79]
	v_pk_add_f32 v[12:13], v[12:13], v[76:77]
	s_waitcnt lgkmcnt(0)
	v_lshlrev_b64 v[16:17], 11, v[112:113]
	global_store_dwordx4 v[114:115], v[12:15], off
	v_cvt_pk_bf16_f32 v248, v12, v13
	v_lshl_add_u64 v[16:17], v[16:17], 0, v[182:183]
	v_mul_f32_e32 v13, v13, v13
	v_fmac_f32_e32 v13, v12, v12
	v_mul_f32_e32 v12, v15, v15
	v_cvt_pk_bf16_f32 v249, v14, v15
	v_lshl_add_u64 v[16:17], v[16:17], 1, s[12:13]
	v_lshl_add_u64 v[16:17], v[16:17], 0, v[252:253]
	v_fmac_f32_e32 v12, v14, v14
	s_waitcnt vmcnt(27)
	v_pk_add_f32 v[10:11], v[10:11], v[74:75]
	v_pk_add_f32 v[8:9], v[8:9], v[72:73]
	v_add_f32_e32 v14, v13, v12
	global_store_dwordx4 v[114:115], v[8:11], off offset:64
	v_cvt_pk_bf16_f32 v250, v8, v9
	s_waitcnt vmcnt(28)
	v_pk_add_f32 v[6:7], v[6:7], v[70:71]
	v_mul_f32_e32 v9, v9, v9
	v_fmac_f32_e32 v9, v8, v8
	v_mul_f32_e32 v8, v11, v11
	v_fmac_f32_e32 v8, v10, v10
	v_pk_add_f32 v[4:5], v[4:5], v[68:69]
	v_cvt_pk_bf16_f32 v251, v10, v11
	v_add_f32_e32 v8, v9, v8
	v_mul_f32_e32 v9, v5, v5
	v_mul_f32_e32 v10, v7, v7
	v_fmac_f32_e32 v9, v4, v4
	v_fmac_f32_e32 v10, v6, v6
	v_add_f32_e32 v8, v14, v8
	v_add_f32_e32 v9, v9, v10
	s_nop 1
	v_permlane16_swap_b32_e32 v248, v250
	v_permlane16_swap_b32_e32 v249, v251
	global_store_dwordx4 v[16:17], v[248:251], off
	s_nop 1
	v_add_f32_e32 v12, v8, v9
	s_waitcnt vmcnt(28)
	v_pk_add_f32 v[10:11], v[2:3], v[66:67]
	v_pk_add_f32 v[8:9], v[0:1], v[64:65]
	v_mul_f32_e32 v1, v11, v11
	v_mul_f32_e32 v0, v9, v9
	v_fmac_f32_e32 v0, v8, v8
	v_fmac_f32_e32 v1, v10, v10
	v_add_f32_e32 v0, v0, v1
	v_add_f32_e32 v2, v12, v0
	ds_bpermute_b32 v3, v126, v2
	v_cvt_pk_bf16_f32 v248, v4, v5
	v_cvt_pk_bf16_f32 v249, v6, v7
	global_store_dwordx4 v[114:115], v[4:7], off offset:512
	s_waitcnt lgkmcnt(0)
	v_add_f32_e32 v0, v2, v3
	ds_bpermute_b32 v1, v127, v0
	v_cvt_pk_bf16_f32 v250, v8, v9
	v_cvt_pk_bf16_f32 v251, v10, v11
	global_store_dwordx4 v[114:115], v[8:11], off offset:576
	s_nop 1
	v_permlane16_swap_b32_e32 v248, v250
	v_permlane16_swap_b32_e32 v249, v251
	global_store_dwordx4 v[16:17], v[248:251], off offset:256
	s_nop 1
	s_and_saveexec_b64 s[24:25], s[6:7]
	s_cbranch_execz .LBB0_150
	v_lshl_add_u64 v[2:3], v[112:113], 2, s[80:81]
	s_waitcnt lgkmcnt(0)
	v_add_f32_e32 v0, v0, v1
	global_atomic_add_f32 v[2:3], v0, off
